# baseline (speedup 1.0000x reference)
; #define LAS __attribute__((address_space(3)))
; __device__ __forceinline__ unsigned pk_bf16(float lo, float hi) { f32x2 v = {lo, hi}; bf16x2_t b = __builtin_convertvector(v, bf16x2_t); return __builtin_bit_cast(unsigned, b); }
; __device__ __forceinline__ float bf_lo(unsigned w) { return __uint_as_float(w << 16); }
; __device__ __forceinline__ float bf_hi(unsigned w) { return __uint_as_float(w & 0xffff0000u); }
; __device__ __forceinline__ float wave_sum(float v) {
; #pragma unroll
;     for (int o = 1; o < 64; o <<= 1) v += __shfl_xor(v, o);
;     return v;
; }
; __device__ __forceinline__ void gmlp_unit(LAS unsigned char* lds, const bf16_t* __restrict__ Zb, const bf16_t* __restrict__ wsp, const float* __restrict__ bsp, bf16_t* __restrict__ mix, int chunk, int g) {
;     ...
; #pragma unroll 4
;     for (int rr = 0; rr < 16; ++rr) {
;         const int q = wid * 16 + rr;
;         const unsigned w = *((const unsigned*)(Zb + (row0 + q) * NIN0 + 1088 + 1024 + g * 128) + lane);
;         const float a = bf_lo(w), c = bf_hi(w);
;         const float mean = wave_sum(a + c) * (1.0f / 128.0f), da = a - mean, dc = c - mean;
;         const float rstd = 1.0f / sqrtf(wave_sum(da * da + dc * dc) * (1.0f / 128.0f) + EPS);
;         *(LAS unsigned*)(lds + q * VS + lane * 4) = pk_bf16(da * rstd, dc * rstd);
;     }
.Lgm_nopf:
	s_cmp_lg_u32 s40, 0x1a000
	v_add_f32_e32 v5, v3, v2
	v_add_f32_e32 v12, v7, v6
	v_add_f32_e32 v13, v9, v8
	v_add_f32_e32 v14, v11, v10
	v_add_f32_dpp v5, v5, v5 quad_perm:[1,0,3,2] row_mask:0xf bank_mask:0xf
	v_add_f32_dpp v12, v12, v12 quad_perm:[1,0,3,2] row_mask:0xf bank_mask:0xf
	v_add_f32_dpp v13, v13, v13 quad_perm:[1,0,3,2] row_mask:0xf bank_mask:0xf
	v_add_f32_dpp v14, v14, v14 quad_perm:[1,0,3,2] row_mask:0xf bank_mask:0xf
	v_add_f32_dpp v5, v5, v5 quad_perm:[2,3,0,1] row_mask:0xf bank_mask:0xf
	v_add_f32_dpp v12, v12, v12 quad_perm:[2,3,0,1] row_mask:0xf bank_mask:0xf
	v_add_f32_dpp v13, v13, v13 quad_perm:[2,3,0,1] row_mask:0xf bank_mask:0xf
	v_add_f32_dpp v14, v14, v14 quad_perm:[2,3,0,1] row_mask:0xf bank_mask:0xf
	v_add_f32_dpp v5, v5, v5 row_half_mirror row_mask:0xf bank_mask:0xf
	v_add_f32_dpp v12, v12, v12 row_half_mirror row_mask:0xf bank_mask:0xf
	v_add_f32_dpp v13, v13, v13 row_half_mirror row_mask:0xf bank_mask:0xf
	v_add_f32_dpp v14, v14, v14 row_half_mirror row_mask:0xf bank_mask:0xf
	v_add_f32_dpp v5, v5, v5 row_mirror row_mask:0xf bank_mask:0xf
	v_add_f32_dpp v12, v12, v12 row_mirror row_mask:0xf bank_mask:0xf
	v_add_f32_dpp v13, v13, v13 row_mirror row_mask:0xf bank_mask:0xf
	v_add_f32_dpp v14, v14, v14 row_mirror row_mask:0xf bank_mask:0xf
	v_mov_b32_e32 v15, v5
	v_mov_b32_e32 v16, v12
	v_mov_b32_e32 v17, v13
	v_mov_b32_e32 v18, v14
	v_permlane16_swap_b32_e32 v5, v15
	v_permlane16_swap_b32_e32 v12, v16
	v_permlane16_swap_b32_e32 v13, v17
	v_permlane16_swap_b32_e32 v14, v18
	v_add_f32_e32 v5, v5, v15
	v_add_f32_e32 v12, v12, v16
	v_add_f32_e32 v13, v13, v17
	v_add_f32_e32 v14, v14, v18
	v_mov_b32_e32 v15, v5
	v_mov_b32_e32 v16, v12
	v_mov_b32_e32 v17, v13
	v_mov_b32_e32 v18, v14
	v_permlane32_swap_b32_e32 v5, v15
	v_permlane32_swap_b32_e32 v12, v16
	v_permlane32_swap_b32_e32 v13, v17
	v_permlane32_swap_b32_e32 v14, v18
	v_add_f32_e32 v5, v5, v15
	v_add_f32_e32 v15, v12, v16
	v_add_f32_e32 v13, v13, v17
	v_add_f32_e32 v17, v14, v18
	v_mul_f32_e32 v12, 0x3c000000, v5
	v_mul_f32_e32 v14, 0x3c000000, v15
	v_mul_f32_e32 v16, 0x3c000000, v13
	v_pk_add_f32 v[2:3], v[2:3], v[12:13] op_sel_hi:[1,0] neg_lo:[0,1] neg_hi:[0,1]
	v_pk_add_f32 v[6:7], v[6:7], v[14:15] op_sel_hi:[1,0] neg_lo:[0,1] neg_hi:[0,1]
	v_pk_add_f32 v[8:9], v[8:9], v[16:17] op_sel_hi:[1,0] neg_lo:[0,1] neg_hi:[0,1]
	v_pk_mul_f32 v[12:13], v[2:3], v[2:3]
	v_mul_f32_e32 v18, 0x3c000000, v17
	v_pk_mul_f32 v[14:15], v[6:7], v[6:7]
	v_pk_mul_f32 v[16:17], v[8:9], v[8:9]
	v_add_f32_e32 v5, v12, v13
	v_add_f32_e32 v12, v14, v15
	v_add_f32_e32 v13, v16, v17
	v_pk_add_f32 v[10:11], v[10:11], v[18:19] op_sel_hi:[1,0] neg_lo:[0,1] neg_hi:[0,1]
	v_pk_mul_f32 v[18:19], v[10:11], v[10:11]
	v_add_f32_e32 v14, v18, v19
	v_add_f32_dpp v5, v5, v5 quad_perm:[1,0,3,2] row_mask:0xf bank_mask:0xf
	v_add_f32_dpp v12, v12, v12 quad_perm:[1,0,3,2] row_mask:0xf bank_mask:0xf
	v_add_f32_dpp v13, v13, v13 quad_perm:[1,0,3,2] row_mask:0xf bank_mask:0xf
	v_add_f32_dpp v14, v14, v14 quad_perm:[1,0,3,2] row_mask:0xf bank_mask:0xf
	v_add_f32_dpp v5, v5, v5 quad_perm:[2,3,0,1] row_mask:0xf bank_mask:0xf
	v_add_f32_dpp v12, v12, v12 quad_perm:[2,3,0,1] row_mask:0xf bank_mask:0xf
	v_add_f32_dpp v13, v13, v13 quad_perm:[2,3,0,1] row_mask:0xf bank_mask:0xf
	v_add_f32_dpp v14, v14, v14 quad_perm:[2,3,0,1] row_mask:0xf bank_mask:0xf
	v_add_f32_dpp v5, v5, v5 row_half_mirror row_mask:0xf bank_mask:0xf
	v_add_f32_dpp v12, v12, v12 row_half_mirror row_mask:0xf bank_mask:0xf
	v_add_f32_dpp v13, v13, v13 row_half_mirror row_mask:0xf bank_mask:0xf
	v_add_f32_dpp v14, v14, v14 row_half_mirror row_mask:0xf bank_mask:0xf
	v_add_f32_dpp v5, v5, v5 row_mirror row_mask:0xf bank_mask:0xf
	v_add_f32_dpp v12, v12, v12 row_mirror row_mask:0xf bank_mask:0xf
	v_add_f32_dpp v13, v13, v13 row_mirror row_mask:0xf bank_mask:0xf
	v_add_f32_dpp v14, v14, v14 row_mirror row_mask:0xf bank_mask:0xf
	v_mov_b32_e32 v15, v5
	v_mov_b32_e32 v16, v12
	v_mov_b32_e32 v17, v13
	v_mov_b32_e32 v18, v14
	v_permlane16_swap_b32_e32 v5, v15
	v_permlane16_swap_b32_e32 v12, v16
	v_permlane16_swap_b32_e32 v13, v17
	v_permlane16_swap_b32_e32 v14, v18
	v_add_f32_e32 v5, v5, v15
	v_add_f32_e32 v12, v12, v16
	v_add_f32_e32 v13, v13, v17
	v_add_f32_e32 v14, v14, v18
	v_mov_b32_e32 v15, v5
	v_mov_b32_e32 v16, v12
	v_mov_b32_e32 v17, v13
	v_mov_b32_e32 v18, v14
	v_permlane32_swap_b32_e32 v5, v15
	v_permlane32_swap_b32_e32 v12, v16
	v_permlane32_swap_b32_e32 v13, v17
	v_permlane32_swap_b32_e32 v14, v18
	v_add_f32_e32 v5, v5, v15
	v_add_f32_e32 v12, v12, v16
	v_add_f32_e32 v13, v13, v17
	v_add_f32_e32 v14, v14, v18
	v_fmamk_f32 v5, v5, 0x3c000000, v95
	v_fmamk_f32 v12, v12, 0x3c000000, v95
	v_fmamk_f32 v13, v13, 0x3c000000, v95
	v_mul_f32_e32 v15, 0x4f800000, v5
	v_cmp_gt_f32_e64 s[4:5], s58, v5
	v_mul_f32_e32 v16, 0x4f800000, v12
	v_cmp_gt_f32_e32 vcc, s58, v12
	v_mul_f32_e32 v17, 0x4f800000, v13
	v_cmp_gt_f32_e64 s[0:1], s58, v13
	v_cndmask_b32_e64 v5, v5, v15, s[4:5]
	v_cndmask_b32_e32 v12, v12, v16, vcc
	v_cndmask_b32_e64 v13, v13, v17, s[0:1]
	v_sqrt_f32_e32 v15, v5
	v_fmamk_f32 v14, v14, 0x3c000000, v95
	v_sqrt_f32_e32 v16, v12
	v_sqrt_f32_e32 v17, v13
	v_mul_f32_e32 v18, 0x4f800000, v14
	v_cmp_gt_f32_e64 s[2:3], s58, v14
	v_add_u32_e32 v19, -1, v15
	v_add_u32_e32 v20, 1, v15
	v_cndmask_b32_e64 v14, v14, v18, s[2:3]
	v_sqrt_f32_e32 v18, v14
	v_add_u32_e32 v21, -1, v16
	v_add_u32_e32 v23, -1, v17
	v_fma_f32 v27, -v19, v15, v5
	v_add_u32_e32 v22, 1, v16
	v_add_u32_e32 v24, 1, v17
	v_fma_f32 v28, -v20, v15, v5
	v_fma_f32 v29, -v21, v16, v12
	v_fma_f32 v31, -v23, v17, v13
	v_cmp_ge_f32_e64 s[10:11], 0, v27
	v_fma_f32 v30, -v22, v16, v12
; #define LAS __attribute__((address_space(3)))
; __device__ __forceinline__ unsigned pk_bf16(float lo, float hi) { f32x2 v = {lo, hi}; bf16x2_t b = __builtin_convertvector(v, bf16x2_t); return __builtin_bit_cast(unsigned, b); }
; __device__ __forceinline__ float bf_lo(unsigned w) { return __uint_as_float(w << 16); }
; __device__ __forceinline__ float bf_hi(unsigned w) { return __uint_as_float(w & 0xffff0000u); }
; #define MFMA32(a, b, c) __builtin_amdgcn_mfma_f32_32x32x16_bf16((a), (b), (c), 0, 0, 0)
; __device__ __forceinline__ void gmlp_unit(LAS unsigned char* lds, const bf16_t* __restrict__ Zb, const bf16_t* __restrict__ wsp, const float* __restrict__ bsp, bf16_t* __restrict__ mix, int chunk, int g) {
;     ...
;         const float a = bf_lo(w), c = bf_hi(w);
;         const float mean = wave_sum(a + c) * (1.0f / 128.0f), da = a - mean, dc = c - mean;
;         const float rstd = 1.0f / sqrtf(wave_sum(da * da + dc * dc) * (1.0f / 128.0f) + EPS);
;         *(LAS unsigned*)(lds + q * VS + lane * 4) = pk_bf16(da * rstd, dc * rstd);
;     }
;     __syncthreads();
;     const int pb = wid >> 1, cb0 = 2 * (wid & 1);
;     f32x16 acc[2];
; #pragma unroll
;     for (int e = 0; e < 16; ++e) { acc[0][e] = 0.f; acc[1][e] = 0.f; }
;     const bf16_t* ap = wsp + (size_t)g * 16384 + (size_t)(32 * pb + r) * 128 + 8 * h;
;     const int vlane = (8 * h + ((lane & 15) >> 2)) * VS + (16 * ((lane >> 4) & 1) + 4 * (lane & 3)) * 2;
; #pragma unroll
;     for (int ks = 0; ks < 8; ++ks) {
;         const bf16x8 af = *(const bf16x8*)(ap + 16 * ks);
; #pragma unroll
;         for (int ci = 0; ci < 2; ++ci) {
;             const LAS unsigned char* vp = lds + vlane + (16 * ks) * VS + (cb0 + ci) * 64;
;             const s16x4 lo = tr_read(vp), hi = tr_read(vp + 4 * VS);
;             const bf16x8 vf = __builtin_shufflevector(lo, hi, 0, 1, 2, 3, 4, 5, 6, 7);
;             acc[ci] = MFMA32(af, vf, acc[ci]);
;         }
;     }
	v_fma_f32 v32, -v24, v17, v13
	v_cndmask_b32_e64 v15, v15, v19, s[10:11]
	v_cmp_ge_f32_e64 s[10:11], 0, v29
	v_cmp_ge_f32_e64 s[12:13], 0, v31
	v_cmp_lt_f32_e64 s[16:17], 0, v28
	v_add_u32_e32 v25, -1, v18
	v_cndmask_b32_e64 v16, v16, v21, s[10:11]
	v_cmp_lt_f32_e64 s[10:11], 0, v30
	v_cndmask_b32_e64 v17, v17, v23, s[12:13]
	v_cmp_lt_f32_e64 s[12:13], 0, v32
	v_cndmask_b32_e64 v15, v15, v20, s[16:17]
	v_add_u32_e32 v26, 1, v18
	v_fma_f32 v33, -v25, v18, v14
	v_cndmask_b32_e64 v16, v16, v22, s[10:11]
	v_cndmask_b32_e64 v17, v17, v24, s[12:13]
	v_mul_f32_e32 v19, 0x37800000, v15
	v_fma_f32 v34, -v26, v18, v14
	v_cmp_ge_f32_e64 s[14:15], 0, v33
	v_mul_f32_e32 v20, 0x37800000, v16
	v_mul_f32_e32 v21, 0x37800000, v17
	v_cndmask_b32_e64 v15, v15, v19, s[4:5]
	v_cmp_class_f32_e64 s[4:5], v5, v96
	v_cndmask_b32_e64 v18, v18, v25, s[14:15]
	v_cmp_lt_f32_e64 s[14:15], 0, v34
	v_cndmask_b32_e32 v16, v16, v20, vcc
	v_cmp_class_f32_e32 vcc, v12, v96
	v_cndmask_b32_e64 v17, v17, v21, s[0:1]
	v_cmp_class_f32_e64 s[0:1], v13, v96
	v_cndmask_b32_e64 v5, v15, v5, s[4:5]
	v_cndmask_b32_e64 v18, v18, v26, s[14:15]
	v_cndmask_b32_e32 v15, v16, v12, vcc
	v_cndmask_b32_e64 v13, v17, v13, s[0:1]
	v_div_scale_f32 v12, s[0:1], v5, v5, 1.0
	v_mul_f32_e32 v22, 0x37800000, v18
	v_div_scale_f32 v17, s[0:1], v15, v15, 1.0
	v_rcp_f32_e32 v23, v12
	v_cndmask_b32_e64 v18, v18, v22, s[2:3]
	v_cmp_class_f32_e64 s[2:3], v14, v96
	v_rcp_f32_e32 v24, v17
	v_fma_f32 v27, -v12, v23, 1.0
	v_cndmask_b32_e64 v14, v18, v14, s[2:3]
	v_div_scale_f32 v19, s[2:3], v13, v13, 1.0
	v_div_scale_f32 v21, s[4:5], v14, v14, 1.0
	v_rcp_f32_e32 v25, v19
	v_rcp_f32_e32 v26, v21
	v_div_scale_f32 v16, vcc, 1.0, v5, 1.0
	v_fma_f32 v28, -v17, v24, 1.0
	v_fmac_f32_e32 v23, v27, v23
	v_div_scale_f32 v18, s[0:1], 1.0, v15, 1.0
	v_fmac_f32_e32 v24, v28, v24
	v_mul_f32_e32 v27, v16, v23
	v_fma_f32 v29, -v19, v25, 1.0
	v_mul_f32_e32 v28, v18, v24
	v_fma_f32 v31, -v12, v27, v16
	v_div_scale_f32 v20, s[2:3], 1.0, v13, 1.0
	v_fma_f32 v30, -v21, v26, 1.0
	v_fmac_f32_e32 v25, v29, v25
	v_fma_f32 v32, -v17, v28, v18
	v_fmac_f32_e32 v27, v31, v23
	v_div_scale_f32 v22, s[4:5], 1.0, v14, 1.0
	v_fmac_f32_e32 v26, v30, v26
	v_mul_f32_e32 v29, v20, v25
	v_fmac_f32_e32 v28, v32, v24
	v_fma_f32 v12, -v12, v27, v16
	v_mul_f32_e32 v30, v22, v26
	v_fma_f32 v33, -v19, v29, v20
	v_fma_f32 v16, -v17, v28, v18
	v_div_fmas_f32 v12, v12, v23, v27
	s_mov_b64 vcc, s[0:1]
	v_fma_f32 v34, -v21, v30, v22
	v_fmac_f32_e32 v29, v33, v25
	v_div_fixup_f32 v12, v12, v5, 1.0
	v_div_fmas_f32 v5, v16, v24, v28
	v_fmac_f32_e32 v30, v34, v26
	v_fma_f32 v17, -v19, v29, v20
	v_pk_mul_f32 v[2:3], v[2:3], v[12:13] op_sel_hi:[1,0]
	v_div_fixup_f32 v12, v5, v15, 1.0
	s_mov_b64 vcc, s[2:3]
	v_fma_f32 v18, -v21, v30, v22
	v_div_fmas_f32 v5, v17, v25, v29
	v_cvt_pk_bf16_f32 v15, v2, v3
	v_pk_mul_f32 v[2:3], v[6:7], v[12:13] op_sel_hi:[1,0]
	s_mov_b64 vcc, s[4:5]
	v_div_fixup_f32 v6, v5, v13, 1.0
	v_div_fmas_f32 v5, v18, v26, v30
	v_cvt_pk_bf16_f32 v7, v2, v3
	v_pk_mul_f32 v[2:3], v[8:9], v[6:7] op_sel_hi:[1,0]
	v_div_fixup_f32 v6, v5, v14, 1.0
	v_cvt_pk_bf16_f32 v5, v2, v3
	v_pk_mul_f32 v[2:3], v[10:11], v[6:7] op_sel_hi:[1,0]
	ds_write2_b32 v4, v15, v7 offset1:80
	v_cvt_pk_bf16_f32 v2, v2, v3
	ds_write2_b32 v4, v5, v2 offset0:160 offset1:240
	v_add_u32_e32 v4, 0x500, v4
	s_cbranch_scc1 .LBB0_618
	s_and_b32 s2, s44, 7
	s_lshl_b64 s[0:1], s[38:39], 7
	s_lshl_b32 s3, s2, 15
	s_add_u32 s4, s45, s3
	s_addc_u32 s5, s54, 0
	s_lshr_b32 s3, s26, 2
	s_and_b32 s3, s3, 0x3fffffe0
	v_or_b32_e32 v48, s3, v166
	v_lshlrev_b64 v[0:1], 8, v[48:49]
	v_lshl_add_u64 v[0:1], s[4:5], 0, v[0:1]
	v_mov_b32_e32 v53, v49
	v_lshl_add_u64 v[58:59], v[0:1], 0, v[52:53]
	global_load_dwordx4 v[0:3], v[58:59], off
	global_load_dwordx4 v[40:43], v[58:59], off offset:32
	global_load_dwordx4 v[32:35], v[58:59], off offset:64
	global_load_dwordx4 v[36:39], v[58:59], off offset:96
	global_load_dwordx4 v[44:47], v[58:59], off offset:128
	global_load_dwordx4 v[62:65], v[58:59], off offset:160
	s_waitcnt lgkmcnt(0)
	s_barrier
	s_lshl_b32 s4, s9, 7
	s_and_b32 s5, s4, 0x80
	v_add_u32_e32 v97, s5, v86
	ds_read_b64_tr_b16 v[4:5], v97
	ds_read_b64_tr_b16 v[6:7], v97 offset:1280
	s_or_b32 s4, s5, 64
	v_add_u32_e32 v134, s4, v86
	ds_read_b64_tr_b16 v[60:61], v97 offset:37120
	v_or_b32_e32 v48, s3, v87
	v_mov_b32_e32 v85, v49
	v_mov_b32_e32 v123, v49
	v_mov_b32_e32 v125, v49
	v_mov_b32_e32 v129, v49
	v_lshl_add_u32 v84, s2, 7, v48
	v_or_b32_e32 v122, 1, v48
	v_or_b32_e32 v124, 2, v48
	v_or_b32_e32 v128, 8, v48
	v_mov_b64_e32 v[54:55], s[20:21]
	v_lshl_add_u64 v[132:133], s[0:1], 0, v[48:49]
	s_lshl_b32 s26, s2, 8
	v_lshlrev_b32_e32 v53, 1, v166
	v_mov_b32_e32 v57, v49
	v_or_b32_e32 v56, s5, v53
	v_mov_b32_e32 v127, v49
	v_or_b32_e32 v126, 3, v48
	v_mov_b32_e32 v131, v49
	v_or_b32_e32 v130, 9, v48
	s_waitcnt vmcnt(5) lgkmcnt(1)
	v_mfma_f32_32x32x16_bf16 v[16:31], v[0:3], v[4:7], 0
	ds_read_b64_tr_b16 v[4:5], v134
	ds_read_b64_tr_b16 v[6:7], v134 offset:1280
	ds_read_b64_tr_b16 v[82:83], v134 offset:37120
	ds_read_b64_tr_b16 v[66:67], v97 offset:5120
	ds_read_b64_tr_b16 v[68:69], v97 offset:6400
	ds_read_b64_tr_b16 v[70:71], v97 offset:10240
	ds_read_b64_tr_b16 v[72:73], v97 offset:11520
	global_load_dwordx4 v[98:101], v[58:59], off offset:192
	s_waitcnt lgkmcnt(5)
	v_mfma_f32_32x32x16_bf16 v[0:15], v[0:3], v[4:7], 0
	s_waitcnt vmcnt(5) lgkmcnt(2)
	v_mfma_f32_32x32x16_bf16 v[16:31], v[40:43], v[66:69], v[16:31]
	ds_read_b64_tr_b16 v[66:67], v134 offset:5120
	ds_read_b64_tr_b16 v[68:69], v134 offset:6400
	ds_read_b64_tr_b16 v[74:75], v134 offset:10240
	ds_read_b64_tr_b16 v[76:77], v134 offset:11520
	s_waitcnt lgkmcnt(2)
; #define LAS __attribute__((address_space(3)))
; __device__ __forceinline__ float bf2f(bf16_t v) { return __uint_as_float((unsigned)v << 16); }
; __device__ __forceinline__ bf16_t f2bf(float f) { return (bf16_t)(pk_bf16(f, 0.f) & 0xffffu); }
; __device__ __forceinline__ int crow(int reg, int h) { return (reg & 3) + 8 * (reg >> 2) + 4 * h; }
; #define MFMA32(a, b, c) __builtin_amdgcn_mfma_f32_32x32x16_bf16((a), (b), (c), 0, 0, 0)
; __device__ __forceinline__ void gmlp_unit(LAS unsigned char* lds, const bf16_t* __restrict__ Zb, const bf16_t* __restrict__ wsp, const float* __restrict__ bsp, bf16_t* __restrict__ mix, int chunk, int g) {
;     ...
; #pragma unroll
;     for (int ks = 0; ks < 8; ++ks) {
;         const bf16x8 af = *(const bf16x8*)(ap + 16 * ks);
; #pragma unroll
;         for (int ci = 0; ci < 2; ++ci) {
;             const LAS unsigned char* vp = lds + vlane + (16 * ks) * VS + (cb0 + ci) * 64;
;             const s16x4 lo = tr_read(vp), hi = tr_read(vp + 4 * VS);
;             const bf16x8 vf = __builtin_shufflevector(lo, hi, 0, 1, 2, 3, 4, 5, 6, 7);
;             acc[ci] = MFMA32(af, vf, acc[ci]);
;         }
;     }
; #pragma unroll
;     for (int ci = 0; ci < 2; ++ci)
; #pragma unroll
;         for (int e = 0; e < 16; ++e) {
;             const int p = 32 * pb + crow(e, h), c = 32 * (cb0 + ci) + r;
;             const float u = bf2f(Zb[(row0 + p) * NIN0 + 1088 + g * 128 + c]);
;             mix[(row0 + p) * DM + 1024 + g * 128 + c] = f2bf(u * (acc[ci][e] + bsp[g * 128 + p]));
	v_mfma_f32_32x32x16_bf16 v[0:15], v[40:43], v[66:69], v[0:15]
	ds_read_b64_tr_b16 v[40:41], v97 offset:15360
	ds_read_b64_tr_b16 v[42:43], v97 offset:16640
	ds_read_b64_tr_b16 v[66:67], v97 offset:20480
	ds_read_b64_tr_b16 v[68:69], v97 offset:21760
	ds_read_b64_tr_b16 v[78:79], v97 offset:25600
	ds_read_b64_tr_b16 v[80:81], v97 offset:26880
	ds_read_b64_tr_b16 v[102:103], v97 offset:30720
	ds_read_b64_tr_b16 v[104:105], v97 offset:32000
	s_waitcnt vmcnt(4)
	v_mfma_f32_32x32x16_bf16 v[16:31], v[32:35], v[70:73], v[16:31]
	ds_read_b64_tr_b16 v[70:71], v134 offset:15360
	ds_read_b64_tr_b16 v[72:73], v134 offset:16640
	ds_read_b64_tr_b16 v[106:107], v134 offset:20480
	ds_read_b64_tr_b16 v[108:109], v134 offset:21760
	global_load_dwordx4 v[110:113], v[58:59], off offset:224
	ds_read_b64_tr_b16 v[114:115], v134 offset:25600
	ds_read_b64_tr_b16 v[116:117], v134 offset:26880
	ds_read_b64_tr_b16 v[118:119], v134 offset:30720
	ds_read_b64_tr_b16 v[120:121], v134 offset:32000
	s_waitcnt lgkmcnt(14)
	v_mfma_f32_32x32x16_bf16 v[0:15], v[32:35], v[74:77], v[0:15]
	v_mad_u64_u32 v[32:33], s[2:3], v132, s64, v[54:55]
	v_mad_i32_i24 v33, v133, s64, v33
	v_lshl_add_u64 v[74:75], v[32:33], 0, s[26:27]
	v_lshl_add_u64 v[32:33], v[74:75], 0, v[56:57]
	global_load_ushort v135, v[32:33], off offset:2176
	s_waitcnt vmcnt(5)
	v_mfma_f32_32x32x16_bf16 v[16:31], v[36:39], v[40:43], v[16:31]
	v_lshl_add_u64 v[40:41], v[84:85], 2, s[36:37]
	v_lshl_add_u64 v[42:43], s[0:1], 0, v[122:123]
	v_lshl_add_u64 v[84:85], s[0:1], 0, v[124:125]
	v_lshl_add_u64 v[124:125], s[0:1], 0, v[128:129]
	v_lshl_add_u64 v[122:123], s[0:1], 0, v[126:127]
	v_lshl_add_u64 v[126:127], s[0:1], 0, v[130:131]
	s_waitcnt lgkmcnt(6)
	v_mfma_f32_32x32x16_bf16 v[0:15], v[36:39], v[70:73], v[0:15]
	v_mad_u64_u32 v[36:37], s[2:3], v42, s64, v[54:55]
	v_mad_i32_i24 v37, v43, s64, v37
	v_lshl_add_u64 v[76:77], v[36:37], 0, s[26:27]
	v_lshl_add_u64 v[36:37], v[76:77], 0, v[56:57]
	global_load_ushort v128, v[36:37], off offset:2176
	s_waitcnt vmcnt(5)
	v_mfma_f32_32x32x16_bf16 v[16:31], v[44:47], v[66:69], v[16:31]
	s_waitcnt lgkmcnt(4)
	v_mfma_f32_32x32x16_bf16 v[0:15], v[44:47], v[106:109], v[0:15]
	v_mad_u64_u32 v[44:45], s[2:3], v124, s64, v[54:55]
	v_mad_i32_i24 v45, v125, s64, v45
	v_lshl_add_u64 v[68:69], v[44:45], 0, s[26:27]
	v_lshl_add_u64 v[44:45], v[68:69], 0, v[56:57]
	global_load_ushort v108, v[44:45], off offset:2176
	global_load_dwordx4 v[32:35], v[40:41], off
	v_mad_u64_u32 v[36:37], s[2:3], v84, s64, v[54:55]
	v_mad_i32_i24 v37, v85, s64, v37
	v_lshl_add_u64 v[72:73], v[36:37], 0, s[26:27]
	v_lshl_add_u64 v[36:37], v[72:73], 0, v[56:57]
	global_load_ushort v106, v[36:37], off offset:2176
	v_mad_u64_u32 v[36:37], s[2:3], v122, s64, v[54:55]
	v_mad_i32_i24 v37, v123, s64, v37
	v_lshl_add_u64 v[70:71], v[36:37], 0, s[26:27]
	s_waitcnt vmcnt(7)
	v_mfma_f32_32x32x16_bf16 v[16:31], v[62:65], v[78:81], v[16:31]
	v_lshl_add_u64 v[36:37], v[70:71], 0, v[56:57]
	global_load_ushort v107, v[36:37], off offset:2176
	v_mad_u64_u32 v[44:45], s[2:3], v126, s64, v[54:55]
	global_load_dwordx4 v[36:39], v[40:41], off offset:32
	v_mad_i32_i24 v45, v127, s64, v45
	v_lshl_add_u64 v[66:67], v[44:45], 0, s[26:27]
	v_lshl_add_u64 v[44:45], v[66:67], 0, v[56:57]
	s_waitcnt vmcnt(8)
	v_mfma_f32_32x32x16_bf16 v[16:31], v[98:101], v[102:105], v[16:31]
	global_load_ushort v104, v[44:45], off offset:2176
	ds_read_b64_tr_b16 v[58:59], v97 offset:35840
	ds_read_b64_tr_b16 v[80:81], v134 offset:35840
	v_mov_b32_e32 v45, v49
	v_or_b32_e32 v44, 10, v48
	s_add_u32 s2, s78, s26
	s_addc_u32 s3, s79, 0
	v_mov_b32_e32 v47, v49
	s_waitcnt lgkmcnt(4)
	v_mfma_f32_32x32x16_bf16 v[0:15], v[62:65], v[114:117], v[0:15]
	v_or_b32_e32 v46, 11, v48
	v_lshl_add_u64 v[62:63], s[2:3], 0, v[56:57]
	v_lshlrev_b64 v[64:65], 12, v[42:43]
	s_add_i32 s44, s44, s28
	s_add_i32 s55, s55, s28
	s_cmpk_lt_i32 s44, 0x480
	s_waitcnt lgkmcnt(2)
	v_mfma_f32_32x32x16_bf16 v[0:15], v[98:101], v[118:121], v[0:15]
	v_lshl_add_u64 v[98:99], s[0:1], 0, v[44:45]
	v_mad_u64_u32 v[44:45], s[6:7], v98, s64, v[54:55]
	v_mad_i32_i24 v45, v99, s64, v45
	v_lshl_add_u64 v[78:79], v[44:45], 0, s[26:27]
	v_lshl_add_u64 v[44:45], v[78:79], 0, v[56:57]
	global_load_ushort v97, v[44:45], off offset:2176
	s_waitcnt vmcnt(9) lgkmcnt(1)
	v_mfma_f32_32x32x16_bf16 v[16:31], v[110:113], v[58:61], v[16:31]
	v_lshlrev_b64 v[44:45], 12, v[132:133]
	v_lshl_add_u64 v[100:101], s[0:1], 0, v[46:47]
	s_waitcnt vmcnt(8)
	v_lshlrev_b32_e32 v58, 16, v135
	v_lshl_add_u64 v[46:47], v[62:63], 0, v[44:45]
	v_mov_b32_e32 v59, v49
	v_lshlrev_b64 v[60:61], 12, v[124:125]
	s_waitcnt vmcnt(5)
	s_nop 3
	v_add_f32_e32 v16, v16, v32
	v_mul_f32_e32 v16, v16, v58
	v_cvt_pk_bf16_f32 v16, v16, s0
	v_or_b32_e32 v58, 16, v48
	global_store_short v[46:47], v16, off offset:2048
	v_mad_u64_u32 v[46:47], s[6:7], v100, s64, v[54:55]
	v_lshl_add_u64 v[102:103], s[0:1], 0, v[58:59]
	v_mad_i32_i24 v47, v101, s64, v47
	v_mad_u64_u32 v[58:59], s[6:7], v102, s64, v[54:55]
	s_waitcnt lgkmcnt(0)
	v_mfma_f32_32x32x16_bf16 v[0:15], v[110:113], v[80:83], v[0:15]
	v_lshl_add_u64 v[80:81], v[46:47], 0, s[26:27]
	v_mad_i32_i24 v59, v103, s64, v59
	v_lshl_add_u64 v[46:47], v[80:81], 0, v[56:57]
	v_lshl_add_u64 v[82:83], v[58:59], 0, s[26:27]
	v_lshl_add_u64 v[58:59], v[82:83], 0, v[56:57]
	global_load_ushort v129, v[46:47], off offset:2176
	global_load_ushort v130, v[58:59], off offset:2176
	v_lshlrev_b32_e32 v16, 16, v128
	v_add_f32_e32 v17, v17, v33
	v_mul_f32_e32 v16, v17, v16
	v_cvt_pk_bf16_f32 v46, v16, s0
	v_lshl_add_u64 v[16:17], v[62:63], 0, v[64:65]
	global_store_short v[16:17], v46, off offset:2048
	s_waitcnt vmcnt(8)
; __device__ __forceinline__ float bf2f(bf16_t v) { return __uint_as_float((unsigned)v << 16); }
; __device__ __forceinline__ bf16_t f2bf(float f) { return (bf16_t)(pk_bf16(f, 0.f) & 0xffffu); }
; __device__ __forceinline__ int crow(int reg, int h) { return (reg & 3) + 8 * (reg >> 2) + 4 * h; }
; __device__ __forceinline__ void gmlp_unit(LAS unsigned char* lds, const bf16_t* __restrict__ Zb, const bf16_t* __restrict__ wsp, const float* __restrict__ bsp, bf16_t* __restrict__ mix, int chunk, int g) {
;     ...
; #pragma unroll
;     for (int ci = 0; ci < 2; ++ci)
; #pragma unroll
;         for (int e = 0; e < 16; ++e) {
;             const int p = 32 * pb + crow(e, h), c = 32 * (cb0 + ci) + r;
;             const float u = bf2f(Zb[(row0 + p) * NIN0 + 1088 + g * 128 + c]);
;             mix[(row0 + p) * DM + 1024 + g * 128 + c] = f2bf(u * (acc[ci][e] + bsp[g * 128 + p]));
;         }
	v_lshlrev_b32_e32 v16, 16, v106
	v_add_f32_e32 v17, v18, v34
	v_mul_f32_e32 v16, v17, v16
	v_lshlrev_b64 v[46:47], 12, v[84:85]
	v_cvt_pk_bf16_f32 v18, v16, s0
	v_lshl_add_u64 v[16:17], v[62:63], 0, v[46:47]
	global_store_short v[16:17], v18, off offset:2048
	s_waitcnt vmcnt(8)
	v_lshlrev_b32_e32 v16, 16, v107
	v_add_f32_e32 v17, v19, v35
	v_mul_f32_e32 v16, v17, v16
	v_lshlrev_b64 v[58:59], 12, v[122:123]
	v_cvt_pk_bf16_f32 v18, v16, s0
	v_lshl_add_u64 v[16:17], v[62:63], 0, v[58:59]
	global_store_short v[16:17], v18, off offset:2048
	v_lshlrev_b32_e32 v16, 16, v108
	s_waitcnt vmcnt(8)
	v_add_f32_e32 v17, v20, v36
	v_mul_f32_e32 v16, v17, v16
	v_cvt_pk_bf16_f32 v18, v16, s0
	v_lshl_add_u64 v[16:17], v[62:63], 0, v[60:61]
	global_store_short v[16:17], v18, off offset:2048
	s_waitcnt vmcnt(8)
	v_lshlrev_b32_e32 v16, 16, v104
	v_add_f32_e32 v17, v21, v37
	v_mul_f32_e32 v16, v17, v16
	v_lshlrev_b64 v[20:21], 12, v[126:127]
	v_cvt_pk_bf16_f32 v112, v16, s0
	v_lshl_add_u64 v[42:43], v[62:63], 0, v[20:21]
	v_or_b32_e32 v84, 17, v48
	v_mov_b32_e32 v85, v49
	global_store_short v[42:43], v112, off offset:2048
	v_or_b32_e32 v42, 19, v48
	v_mov_b32_e32 v43, v49
	v_lshl_add_u64 v[104:105], s[0:1], 0, v[84:85]
	v_lshl_add_u64 v[112:113], s[0:1], 0, v[42:43]
	v_mad_u64_u32 v[84:85], s[6:7], v104, s64, v[54:55]
	v_mad_u64_u32 v[42:43], s[6:7], v112, s64, v[54:55]
	v_mad_i32_i24 v85, v105, s64, v85
	v_mad_i32_i24 v43, v113, s64, v43
	global_load_dwordx4 v[16:19], v[40:41], off offset:64
	v_lshl_add_u64 v[106:107], v[84:85], 0, s[26:27]
	v_lshl_add_u64 v[114:115], v[42:43], 0, s[26:27]
	v_lshl_add_u64 v[84:85], v[106:107], 0, v[56:57]
	v_lshl_add_u64 v[42:43], v[114:115], 0, v[56:57]
	global_load_ushort v128, v[84:85], off offset:2176
	global_load_ushort v132, v[42:43], off offset:2176
	v_or_b32_e32 v84, 18, v48
	v_mov_b32_e32 v85, v49
	v_lshl_add_u64 v[108:109], s[0:1], 0, v[84:85]
	v_mad_u64_u32 v[84:85], s[6:7], v108, s64, v[54:55]
	v_mad_i32_i24 v85, v109, s64, v85
	v_lshl_add_u64 v[110:111], v[84:85], 0, s[26:27]
	v_lshl_add_u64 v[84:85], v[110:111], 0, v[56:57]
	global_load_ushort v131, v[84:85], off offset:2176
	v_or_b32_e32 v42, 24, v48
	v_mov_b32_e32 v43, v49
	v_lshl_add_u64 v[116:117], s[0:1], 0, v[42:43]
	v_mad_u64_u32 v[42:43], s[6:7], v116, s64, v[54:55]
	v_or_b32_e32 v84, 25, v48
	v_mov_b32_e32 v85, v49
	v_mad_i32_i24 v43, v117, s64, v43
	v_lshl_add_u64 v[120:121], s[0:1], 0, v[84:85]
	v_lshl_add_u64 v[118:119], v[42:43], 0, s[26:27]
	v_mad_u64_u32 v[84:85], s[6:7], v120, s64, v[54:55]
	v_lshl_add_u64 v[42:43], v[118:119], 0, v[56:57]
	v_mad_i32_i24 v85, v121, s64, v85
	global_load_ushort v133, v[42:43], off offset:2176
	s_nop 0
	global_load_dwordx4 v[40:43], v[40:41], off offset:96
	v_lshl_add_u64 v[122:123], v[84:85], 0, s[26:27]
	v_lshl_add_u64 v[84:85], v[122:123], 0, v[56:57]
	global_load_ushort v134, v[84:85], off offset:2176
	v_or_b32_e32 v84, 26, v48
	v_mov_b32_e32 v85, v49
	v_lshl_add_u64 v[124:125], s[0:1], 0, v[84:85]
	v_mad_u64_u32 v[84:85], s[6:7], v124, s64, v[54:55]
	v_mad_i32_i24 v85, v125, s64, v85
	v_lshl_add_u64 v[126:127], v[84:85], 0, s[26:27]
	s_waitcnt vmcnt(15)
	v_lshlrev_b32_e32 v97, 16, v97
	v_add_f32_e32 v22, v22, v38
	v_lshl_add_u64 v[84:85], v[126:127], 0, v[56:57]
	v_mul_f32_e32 v22, v22, v97
	global_load_ushort v97, v[84:85], off offset:2176
	v_lshlrev_b64 v[84:85], 12, v[98:99]
	v_cvt_pk_bf16_f32 v22, v22, s0
	v_lshl_add_u64 v[98:99], v[62:63], 0, v[84:85]
	v_or_b32_e32 v48, 27, v48
	global_store_short v[98:99], v22, off offset:2048
	v_lshl_add_u64 v[98:99], s[0:1], 0, v[48:49]
	v_mad_u64_u32 v[54:55], s[0:1], v98, s64, v[54:55]
	v_mad_i32_i24 v55, v99, s64, v55
	v_lshl_add_u64 v[54:55], v[54:55], 0, s[26:27]
	v_lshl_add_u64 v[56:57], v[54:55], 0, v[56:57]
	global_load_ushort v135, v[56:57], off offset:2176
	s_waitcnt vmcnt(16)
	v_lshlrev_b32_e32 v22, 16, v129
	v_add_f32_e32 v23, v23, v39
	v_mul_f32_e32 v22, v23, v22
	v_cvt_pk_bf16_f32 v48, v22, s0
	v_lshlrev_b64 v[22:23], 12, v[100:101]
	v_lshl_add_u64 v[56:57], v[62:63], 0, v[22:23]
	global_store_short v[56:57], v48, off offset:2048
	v_or_b32_e32 v48, s4, v53
	v_lshl_add_u64 v[56:57], v[74:75], 0, v[48:49]
	global_load_ushort v53, v[56:57], off offset:2176
	s_waitcnt vmcnt(17)
	v_lshlrev_b32_e32 v100, 16, v130
	v_lshl_add_u64 v[70:71], v[70:71], 0, v[48:49]
	v_lshl_add_u64 v[72:73], v[72:73], 0, v[48:49]
	v_lshl_add_u64 v[66:67], v[66:67], 0, v[48:49]
	v_add_f32_e32 v0, v0, v32
	v_add_f32_e32 v1, v1, v33
	v_lshl_add_u64 v[32:33], v[54:55], 0, v[48:49]
	global_load_ushort v32, v[32:33], off offset:2176
	s_waitcnt vmcnt(12)
	v_add_f32_e32 v24, v24, v16
	v_mul_f32_e32 v24, v24, v100
	global_load_ushort v100, v[70:71], off offset:2176
	v_lshlrev_b64 v[56:57], 12, v[102:103]
	v_cvt_pk_bf16_f32 v24, v24, s0
	v_lshl_add_u64 v[74:75], v[62:63], 0, v[56:57]
	global_store_short v[74:75], v24, off offset:2048
	s_waitcnt vmcnt(13)
	v_lshlrev_b32_e32 v24, 16, v128
	v_lshl_add_u64 v[74:75], v[76:77], 0, v[48:49]
	v_add_f32_e32 v25, v25, v17
	global_load_ushort v76, v[74:75], off offset:2176
	v_mul_f32_e32 v24, v25, v24
	v_cvt_pk_bf16_f32 v77, v24, s0
	v_lshlrev_b64 v[24:25], 12, v[104:105]
	v_lshl_add_u64 v[74:75], v[62:63], 0, v[24:25]
	global_store_short v[74:75], v77, off offset:2048
	global_load_ushort v77, v[72:73], off offset:2176
	s_waitcnt vmcnt(14)
	v_lshlrev_b32_e32 v74, 16, v131
	v_add_f32_e32 v26, v26, v18
	v_mul_f32_e32 v26, v26, v74
	global_load_ushort v102, v[66:67], off offset:2176
	v_lshlrev_b64 v[72:73], 12, v[108:109]
	v_cvt_pk_bf16_f32 v26, v26, s0
	v_lshl_add_u64 v[74:75], v[62:63], 0, v[72:73]
	global_store_short v[74:75], v26, off offset:2048
	v_lshlrev_b32_e32 v26, 16, v132
	v_add_f32_e32 v27, v27, v19
	v_mul_f32_e32 v70, v27, v26
	v_lshl_add_u64 v[26:27], v[68:69], 0, v[48:49]
	global_load_ushort v101, v[26:27], off offset:2176
	s_waitcnt vmcnt(16)
; __device__ __forceinline__ float bf2f(bf16_t v) { return __uint_as_float((unsigned)v << 16); }
; __device__ __forceinline__ bf16_t f2bf(float f) { return (bf16_t)(pk_bf16(f, 0.f) & 0xffffu); }
; __device__ __forceinline__ int crow(int reg, int h) { return (reg & 3) + 8 * (reg >> 2) + 4 * h; }
; __device__ __forceinline__ void gmlp_unit(LAS unsigned char* lds, const bf16_t* __restrict__ Zb, const bf16_t* __restrict__ wsp, const float* __restrict__ bsp, bf16_t* __restrict__ mix, int chunk, int g) {
;     ...
; #pragma unroll
;     for (int ci = 0; ci < 2; ++ci)
; #pragma unroll
;         for (int e = 0; e < 16; ++e) {
;             const int p = 32 * pb + crow(e, h), c = 32 * (cb0 + ci) + r;
;             const float u = bf2f(Zb[(row0 + p) * NIN0 + 1088 + g * 128 + c]);
;             mix[(row0 + p) * DM + 1024 + g * 128 + c] = f2bf(u * (acc[ci][e] + bsp[g * 128 + p]));
;         }
;     __syncthreads();
; __global__ void __launch_bounds__(512, 2) mk_fwd(Args args) {
;     ...
;         for (int j = (F.vcu + F.G - 64) % F.G; j < 1152; j += F.G) gmlp_unit(F.lds, Zb, (const bf16_t*)(ws + WS_WSP), args.in[16], MIXb, j >> 3, j & 7);
	v_lshlrev_b32_e32 v66, 16, v133
	s_waitcnt vmcnt(15)
	v_add_f32_e32 v28, v28, v40
	v_lshlrev_b64 v[26:27], 12, v[112:113]
	v_mul_f32_e32 v28, v28, v66
	v_lshl_add_u64 v[66:67], v[78:79], 0, v[48:49]
	v_lshl_add_u64 v[74:75], v[110:111], 0, v[48:49]
	v_cvt_pk_bf16_f32 v70, v70, s0
	v_lshl_add_u64 v[68:69], v[62:63], 0, v[26:27]
	global_load_ushort v78, v[66:67], off offset:2176
	v_cvt_pk_bf16_f32 v28, v28, s0
	global_load_ushort v74, v[74:75], off offset:2176
	v_lshlrev_b64 v[66:67], 12, v[116:117]
	global_store_short v[68:69], v70, off offset:2048
	v_lshl_add_u64 v[68:69], v[62:63], 0, v[66:67]
	global_store_short v[68:69], v28, off offset:2048
	v_lshl_add_u64 v[68:69], v[80:81], 0, v[48:49]
	global_load_ushort v79, v[68:69], off offset:2176
	s_waitcnt vmcnt(19)
	v_lshlrev_b32_e32 v28, 16, v134
	v_add_f32_e32 v29, v29, v41
	v_mul_f32_e32 v28, v29, v28
	v_lshl_add_u64 v[68:69], v[82:83], 0, v[48:49]
	v_cvt_pk_bf16_f32 v70, v28, s0
	v_lshlrev_b64 v[28:29], 12, v[120:121]
	global_load_ushort v80, v[68:69], off offset:2176
	v_lshl_add_u64 v[68:69], v[62:63], 0, v[28:29]
	global_store_short v[68:69], v70, off offset:2048
	v_lshl_add_u64 v[68:69], v[106:107], 0, v[48:49]
	global_load_ushort v81, v[68:69], off offset:2176
	s_waitcnt vmcnt(21)
	v_lshlrev_b32_e32 v70, 16, v97
	v_add_f32_e32 v30, v30, v42
	v_mul_f32_e32 v30, v30, v70
	v_lshlrev_b64 v[68:69], 12, v[124:125]
	v_cvt_pk_bf16_f32 v30, v30, s0
	v_lshl_add_u64 v[70:71], v[62:63], 0, v[68:69]
	global_store_short v[70:71], v30, off offset:2048
	s_waitcnt vmcnt(20)
	v_lshlrev_b32_e32 v30, 16, v135
	v_add_f32_e32 v31, v31, v43
	v_mul_f32_e32 v70, v31, v30
	v_lshl_add_u64 v[30:31], v[114:115], 0, v[48:49]
	global_load_ushort v75, v[30:31], off offset:2176
	v_lshlrev_b64 v[30:31], 12, v[98:99]
	v_cvt_pk_bf16_f32 v70, v70, s0
	v_lshl_add_u64 v[62:63], v[62:63], 0, v[30:31]
	global_store_short v[62:63], v70, off offset:2048
	v_lshl_add_u64 v[62:63], v[118:119], 0, v[48:49]
	global_load_ushort v82, v[62:63], off offset:2176
	s_waitcnt vmcnt(21)
	v_lshlrev_b32_e32 v53, 16, v53
	v_lshl_add_u64 v[70:71], v[122:123], 0, v[48:49]
	v_lshl_add_u64 v[62:63], s[2:3], 0, v[48:49]
	v_mul_f32_e32 v0, v0, v53
	global_load_ushort v53, v[70:71], off offset:2176
	v_cvt_pk_bf16_f32 v0, v0, s0
	v_lshl_add_u64 v[44:45], v[62:63], 0, v[44:45]
	global_store_short v[44:45], v0, off offset:2048
	v_lshl_add_u64 v[44:45], v[126:127], 0, v[48:49]
	global_load_ushort v44, v[44:45], off offset:2176
	s_waitcnt vmcnt(20)
	v_lshlrev_b32_e32 v0, 16, v76
	v_mul_f32_e32 v0, v1, v0
	v_cvt_pk_bf16_f32 v45, v0, s0
	v_lshl_add_u64 v[0:1], v[62:63], 0, v[64:65]
	global_store_short v[0:1], v45, off offset:2048
	v_add_f32_e32 v1, v2, v34
	s_waitcnt vmcnt(19)
	v_lshlrev_b32_e32 v0, 16, v77
	v_mul_f32_e32 v0, v1, v0
	v_cvt_pk_bf16_f32 v2, v0, s0
	v_lshl_add_u64 v[0:1], v[62:63], 0, v[46:47]
	global_store_short v[0:1], v2, off offset:2048
	v_lshlrev_b32_e32 v0, 16, v100
	v_add_f32_e32 v1, v3, v35
	v_mul_f32_e32 v0, v1, v0
	v_cvt_pk_bf16_f32 v2, v0, s0
	v_lshl_add_u64 v[0:1], v[62:63], 0, v[58:59]
	global_store_short v[0:1], v2, off offset:2048
	v_add_f32_e32 v1, v4, v36
	s_waitcnt vmcnt(18)
	v_lshlrev_b32_e32 v0, 16, v101
	v_mul_f32_e32 v0, v1, v0
	v_cvt_pk_bf16_f32 v2, v0, s0
	v_lshl_add_u64 v[0:1], v[62:63], 0, v[60:61]
	global_store_short v[0:1], v2, off offset:2048
	v_lshlrev_b32_e32 v0, 16, v102
	v_add_f32_e32 v1, v5, v37
	v_mul_f32_e32 v0, v1, v0
	v_cvt_pk_bf16_f32 v2, v0, s0
	v_lshl_add_u64 v[0:1], v[62:63], 0, v[20:21]
	global_store_short v[0:1], v2, off offset:2048
	s_waitcnt vmcnt(19)
	v_lshlrev_b32_e32 v0, 16, v78
	v_add_f32_e32 v1, v6, v38
	v_mul_f32_e32 v0, v1, v0
	v_cvt_pk_bf16_f32 v2, v0, s0
	v_lshl_add_u64 v[0:1], v[62:63], 0, v[84:85]
	global_store_short v[0:1], v2, off offset:2048
	s_waitcnt vmcnt(16)
	v_lshlrev_b32_e32 v0, 16, v79
	v_add_f32_e32 v1, v7, v39
	v_mul_f32_e32 v0, v1, v0
	v_cvt_pk_bf16_f32 v2, v0, s0
	v_lshl_add_u64 v[0:1], v[62:63], 0, v[22:23]
	global_store_short v[0:1], v2, off offset:2048
	v_add_f32_e32 v1, v8, v16
	s_waitcnt vmcnt(16)
	v_lshlrev_b32_e32 v0, 16, v80
	v_mul_f32_e32 v0, v1, v0
	v_cvt_pk_bf16_f32 v2, v0, s0
	v_lshl_add_u64 v[0:1], v[62:63], 0, v[56:57]
	global_store_short v[0:1], v2, off offset:2048
	s_waitcnt vmcnt(15)
	v_lshlrev_b32_e32 v0, 16, v81
	v_add_f32_e32 v1, v9, v17
	v_mul_f32_e32 v0, v1, v0
	v_cvt_pk_bf16_f32 v2, v0, s0
	v_lshl_add_u64 v[0:1], v[62:63], 0, v[24:25]
	global_store_short v[0:1], v2, off offset:2048
	v_lshlrev_b32_e32 v0, 16, v74
	v_add_f32_e32 v1, v10, v18
	v_mul_f32_e32 v0, v1, v0
	v_cvt_pk_bf16_f32 v2, v0, s0
	v_lshl_add_u64 v[0:1], v[62:63], 0, v[72:73]
	global_store_short v[0:1], v2, off offset:2048
	s_waitcnt vmcnt(15)
	v_lshlrev_b32_e32 v0, 16, v75
	v_add_f32_e32 v1, v11, v19
	v_mul_f32_e32 v0, v1, v0
	v_cvt_pk_bf16_f32 v2, v0, s0
	v_lshl_add_u64 v[0:1], v[62:63], 0, v[26:27]
	global_store_short v[0:1], v2, off offset:2048
	s_waitcnt vmcnt(14)
	v_lshlrev_b32_e32 v0, 16, v82
	v_add_f32_e32 v1, v12, v40
	v_mul_f32_e32 v0, v1, v0
	v_cvt_pk_bf16_f32 v2, v0, s0
	v_lshl_add_u64 v[0:1], v[62:63], 0, v[66:67]
	global_store_short v[0:1], v2, off offset:2048
	s_waitcnt vmcnt(14)
	v_lshlrev_b32_e32 v0, 16, v53
	v_add_f32_e32 v1, v13, v41
	v_mul_f32_e32 v0, v1, v0
	v_cvt_pk_bf16_f32 v2, v0, s0
	v_lshl_add_u64 v[0:1], v[62:63], 0, v[28:29]
	global_store_short v[0:1], v2, off offset:2048
	s_waitcnt vmcnt(13)
	v_lshlrev_b32_e32 v0, 16, v44
	v_add_f32_e32 v1, v14, v42
	v_mul_f32_e32 v0, v1, v0
	v_cvt_pk_bf16_f32 v2, v0, s0
	v_lshl_add_u64 v[0:1], v[62:63], 0, v[68:69]
	global_store_short v[0:1], v2, off offset:2048
	v_lshlrev_b32_e32 v0, 16, v32
	v_add_f32_e32 v1, v15, v43
	v_mul_f32_e32 v0, v1, v0
	v_cvt_pk_bf16_f32 v2, v0, s0
	v_lshl_add_u64 v[0:1], v[62:63], 0, v[30:31]
	global_store_short v[0:1], v2, off offset:2048
	s_barrier
	s_cbranch_scc1 .LBB0_617
